# SSD next-chunk prefetch: one exec guard, three address bases with immediate row offsets, no zero-init of the 32 raw registers (on top of rope prefetch)
# speedup vs baseline: 1.0039x; 1.0039x over previous
; #define SD_DLOAD(chx) do { const int tlo_ = dir ? S - 128 * ((chx) + 1) : 128 * (chx), t0_ = tlo_ + rg * 8; \
;         _Pragma("unroll") for (int q = 0; q < 8; ++q) { raw[q] = (u32x4){0u, 0u, 0u, 0u}; \
;             if (tid < 384) raw[q] = *(const u32x4*)(Pb + (size_t)(t0_ + q) * 768 + gcol); } } while (0)
; DI void ssd_item(const Params& p, const Ctx& c, int l, int S, int tokbase, int dir, int head) {
;     ...
;         if (ch + 1 < nch) SD_DLOAD(ch + 1);
.LBB0_397:
	s_or_b64 exec, exec, s[40:41]
	s_add_i32 s24, s2, 1
	s_cmp_ge_u32 s24, s34
	s_cselect_b64 s[40:41], -1, 0
	s_and_b64 vcc, exec, s[40:41]
	s_waitcnt lgkmcnt(0)
	s_barrier
	s_cbranch_vccnz .LBB0_415
	s_lshl_b32 s25, s2, 7
	s_sub_i32 s25, s95, s25
	s_lshl_b32 s26, s24, 7
	s_and_b64 s[70:71], s[44:45], exec
	s_waitcnt vmcnt(6)
	s_cselect_b32 s25, s26, s25
	v_or_b32_e32 v44, s25, v76
	s_and_saveexec_b64 s[70:71], s[46:47]
	s_cbranch_execz .LBB0_414
	v_mad_i64_i32 v[2:3], s[84:85], v44, s28, v[68:69]
	global_load_dwordx4 v[4:7], v[2:3], off
	global_load_dwordx4 v[8:11], v[2:3], off offset:1536
	global_load_dwordx4 v[12:15], v[2:3], off offset:3072
	v_add_co_u32_e32 v2, vcc, 0x1200, v2
	s_nop 1
	v_addc_co_u32_e32 v3, vcc, 0, v3, vcc
	global_load_dwordx4 v[16:19], v[2:3], off
	global_load_dwordx4 v[20:23], v[2:3], off offset:1536
	global_load_dwordx4 v[24:27], v[2:3], off offset:3072
	v_add_co_u32_e32 v2, vcc, 0x1200, v2
	s_nop 1
	v_addc_co_u32_e32 v3, vcc, 0, v3, vcc
	global_load_dwordx4 v[28:31], v[2:3], off
	global_load_dwordx4 v[32:35], v[2:3], off offset:1536
